# EpiConv epilogue: pass-0 conv weight/bias loads issued early (6 before the rstd barrier, 2 right after their target accumulators are consumed) so their round trip overlaps the barriers
# baseline (speedup 1.0000x reference)
;     __device__ __forceinline__ void operator()(f32x4 (&acc)[2][2][4][2], const Unit& u, int wr, int wc, int fr, int fq, PG8_LAS unsigned char* lds, int wid, int lane) const {
;     ...
;         const int grow0 = 254 * u.pm - 2;
;         { const int t = wid * 64 + lane; if (t < 256) { const int gr = grow0 + t; tbl[t] = (gr >= 0 && gr < 8192) ? row_rstd(ss, gr) : 0.f; } }
;         const int j0 = u.pn * 128 + wc * 32 + 8 * fq;
;         asm volatile("s_waitcnt lgkmcnt(0)" ::: "memory"); __builtin_amdgcn_s_barrier(); asm volatile("" ::: "memory");
; #pragma unroll
;         for (int ai = 0; ai < 2; ++ai)
; #pragma unroll
;             for (int m = 0; m < 4; ++m) { const float rs = tbl[ai * HALF + wr * 64 + m * 16 + fr];
; #pragma unroll
;                 for (int bj = 0; bj < 2; ++bj)
; #pragma unroll
;                     for (int n = 0; n < 2; ++n) acc[ai][bj][m][n] = acc[ai][bj][m][n] * rs; }
;     ...
;                 for (int k = 0; k < 3; ++k) w[bj][k] = *(const f32x4*)(cw + k * 11008 + bj * 5504 + j0 + 4 * n);
;                 bs[bj] = *(const f32x4*)(cb + bj * 5504 + j0 + 4 * n); }
.LBB0_372:
	s_or_b64 exec, exec, s[86:87]
	s_lshl_b32 s98, s20, 7
	v_or_b32_e32 v216, s98, v232
	v_ashrrev_i32_e32 v217, 31, v216
	v_lshlrev_b64 v[216:217], 2, v[216:217]
	v_lshl_add_u64 v[202:203], s[16:17], 0, v[216:217]
	v_lshl_add_u64 v[200:201], s[22:23], 0, v[216:217]
	v_add_co_u32_e32 v216, vcc, 0xa000, v202
	s_nop 1
	v_addc_co_u32_e32 v217, vcc, 0, v203, vcc
	v_add_co_u32_e32 v224, vcc, 0x15000, v202
	global_load_dwordx4 v[126:129], v[202:203], off
	s_nop 0
	v_addc_co_u32_e32 v225, vcc, 0, v203, vcc
	global_load_dwordx4 v[134:137], v[216:217], off offset:3072
	global_load_dwordx4 v[130:133], v[224:225], off offset:2048
	global_load_dwordx4 v[142:145], v[200:201], off
	s_mov_b32 s99, 0x10000
	s_nop 0
	v_add_co_u32_e32 v204, vcc, s99, v202
	s_nop 1
	v_addc_co_u32_e32 v205, vcc, 0, v203, vcc
	v_add_co_u32_e32 v216, vcc, 0x1a000, v202
	s_nop 1
	v_addc_co_u32_e32 v217, vcc, 0, v203, vcc
	global_load_dwordx4 v[122:125], v[216:217], off offset:3584
	v_add_co_u32_e32 v216, vcc, 0x5000, v200
	s_nop 1
	v_addc_co_u32_e32 v217, vcc, 0, v201, vcc
	global_load_dwordx4 v[138:141], v[216:217], off offset:1536
	s_waitcnt lgkmcnt(0)
	s_barrier
	ds_read2_b32 v[194:195], v239 offset0:32 offset1:48
	ds_read2_b32 v[188:189], v239 offset0:160 offset1:176
	ds_read2_b32 v[198:199], v239 offset1:16
	ds_read2_b32 v[192:193], v239 offset0:128 offset1:144
	s_waitcnt lgkmcnt(0)
	v_mov_b32_e32 v0, v195
	v_pk_mul_f32 v[168:169], v[118:119], v[0:1] op_sel_hi:[1,0]
	v_pk_mul_f32 v[166:167], v[116:117], v[0:1] op_sel_hi:[1,0]
	v_pk_mul_f32 v[70:71], v[70:71], v[0:1] op_sel_hi:[1,0]
	v_pk_mul_f32 v[68:69], v[68:69], v[0:1] op_sel_hi:[1,0]
	v_pk_mul_f32 v[164:165], v[114:115], v[0:1] op_sel_hi:[1,0]
	v_pk_mul_f32 v[162:163], v[112:113], v[0:1] op_sel_hi:[1,0]
	v_pk_mul_f32 v[66:67], v[66:67], v[0:1] op_sel_hi:[1,0]
	v_pk_mul_f32 v[64:65], v[64:65], v[0:1] op_sel_hi:[1,0]
	v_add_co_u32_e32 v112, vcc, 0x5000, v202
	s_nop 1
	v_addc_co_u32_e32 v113, vcc, 0, v203, vcc
	global_load_dwordx4 v[114:117], v[112:113], off offset:1536
	global_load_dwordx4 v[118:121], v[204:205], off offset:512
	v_mov_b32_e32 v0, v189
	v_mov_b32_e32 v196, v199
	v_mov_b32_e32 v190, v193
	v_pk_mul_f32 v[110:111], v[110:111], v[0:1] op_sel_hi:[1,0]
	v_pk_mul_f32 v[108:109], v[108:109], v[0:1] op_sel_hi:[1,0]
	v_pk_mul_f32 v[46:47], v[46:47], v[0:1] op_sel_hi:[1,0]
	v_pk_mul_f32 v[44:45], v[44:45], v[0:1] op_sel_hi:[1,0]
	v_pk_mul_f32 v[106:107], v[106:107], v[0:1] op_sel_hi:[1,0]
	v_pk_mul_f32 v[104:105], v[104:105], v[0:1] op_sel_hi:[1,0]
	v_pk_mul_f32 v[42:43], v[42:43], v[0:1] op_sel_hi:[1,0]
	v_pk_mul_f32 v[40:41], v[40:41], v[0:1] op_sel_hi:[1,0]
	s_and_saveexec_b64 s[0:1], s[40:41]
	s_cbranch_execz .LBB0_377
	v_readlane_b32 s38, v253, 13
	v_readlane_b32 s39, v253, 14
	s_andn2_b64 vcc, exec, s[38:39]
	s_cbranch_vccnz .LBB0_375
	ds_write_b128 v233, v[166:169]
	ds_write_b128 v233, v[68:71] offset:16
	ds_write_b128 v233, v[162:165] offset:512
	ds_write_b128 v233, v[64:67] offset:528

; #define PG8_LAS __attribute__((address_space(3)))
;     __device__ __forceinline__ void operator()(f32x4 (&acc)[2][2][4][2], const Unit& u, int wr, int wc, int fr, int fq, PG8_LAS unsigned char* lds, int wid, int lane) const {
;     ...
;         if (fr >= 14) {
; #pragma unroll
;             for (int ai = 0; ai < 2; ++ai) { const int b = 2 * ai + wr; if (b < 3) {
; #pragma unroll
;                 for (int bj = 0; bj < 2; ++bj)
; #pragma unroll
;                     for (int n = 0; n < 2; ++n) *(PG8_LAS f32x4*)(X + (b * 2 + fr - 14) * 256 + bj * HALF + wc * 32 + 8 * fq + 4 * n) = acc[ai][bj][3][n]; } }
;         }
;         asm volatile("s_waitcnt lgkmcnt(0)" ::: "memory"); __builtin_amdgcn_s_barrier(); asm volatile("" ::: "memory");
;         unsigned pk0[2][4][2];
; #pragma unroll
;         for (int n = 0; n < 2; ++n) {
;             f32x4 w[2][3], bs[2];
; #pragma unroll
;             for (int bj = 0; bj < 2; ++bj) {
; #pragma unroll
;                 for (int k = 0; k < 3; ++k) w[bj][k] = *(const f32x4*)(cw + k * 11008 + bj * 5504 + j0 + 4 * n);
;                 bs[bj] = *(const f32x4*)(cb + bj * 5504 + j0 + 4 * n); }
; #pragma unroll
;             for (int ai = 0; ai < 2; ++ai) { const int b = 2 * ai + wr;
; #pragma unroll
;                 for (int m = 0; m < 4; ++m) { f32x4 c[2];
; #pragma unroll
;                     for (int bj = 0; bj < 2; ++bj) { const f32x4 cur = acc[ai][bj][m][n]; f32x4 prev;
;                         if (m > 0) prev = acc[ai][bj][m > 0 ? m - 1 : 0][n];
;                         else { prev = (f32x4){0.f, 0.f, 0.f, 0.f}; if (b > 0 && fr >= 14) prev = *(const PG8_LAS f32x4*)(X + ((b - 1) * 2 + fr - 14) * 256 + bj * HALF + wc * 32 + 8 * fq + 4 * n); }
;                         f32x4 p1, p2;
; #pragma unroll
;                         for (int j = 0; j < 4; ++j) { const float r1 = PG8_ROR(prev[j], 0x121), r2 = PG8_ROR(prev[j], 0x122);
;                             p1[j] = PG8_DPP(r1, cur[j], 0x111); p2[j] = PG8_DPP(r2, cur[j], 0x112); }
;                         c[bj] = bs[bj] + w[bj][0] * p2 + w[bj][1] * p1 + w[bj][2] * cur; }
;                     float h4[4];
; #pragma unroll
;                     for (int j = 0; j < 4; ++j) h4[j] = c[0][j] * __builtin_amdgcn_rcpf(1.0f + __expf(-c[0][j])) * c[1][j];
.LBB0_377:
	s_or_b64 exec, exec, s[0:1]
	s_lshl_b32 s0, s20, 7
	s_mov_b32 s1, 0x10000
	s_waitcnt lgkmcnt(0)
	s_barrier
	s_nop 0
	v_mov_b32_e32 v170, 0
	v_mov_b32_e32 v172, 0
	v_mov_b32_e32 v173, 0
	v_mov_b32_e32 v174, 0
	v_mov_b32_e32 v175, 0
	s_and_saveexec_b64 s[86:87], s[78:79]
	ds_read_b128 v[172:175], v236
	s_or_b64 exec, exec, s[86:87]
	v_pk_mul_f32 v[160:161], v[160:161], v[198:199] op_sel_hi:[1,0]
	v_pk_mul_f32 v[158:159], v[158:159], v[198:199] op_sel_hi:[1,0]
	s_waitcnt lgkmcnt(0)
	v_mov_b32_dpp v112, v172 row_ror:1 row_mask:0xf bank_mask:0xf bound_ctrl:1
	v_mov_b32_dpp v206, v172 row_ror:2 row_mask:0xf bank_mask:0xf bound_ctrl:1
	v_mov_b32_dpp v113, v173 row_ror:1 row_mask:0xf bank_mask:0xf bound_ctrl:1
	v_mov_b32_dpp v207, v173 row_ror:2 row_mask:0xf bank_mask:0xf bound_ctrl:1
	v_mov_b32_dpp v208, v174 row_ror:1 row_mask:0xf bank_mask:0xf bound_ctrl:1
	v_mov_b32_dpp v174, v174 row_ror:2 row_mask:0xf bank_mask:0xf bound_ctrl:1
	v_mov_b32_dpp v209, v175 row_ror:1 row_mask:0xf bank_mask:0xf bound_ctrl:1
	v_mov_b32_dpp v175, v175 row_ror:2 row_mask:0xf bank_mask:0xf bound_ctrl:1
	v_mov_b32_dpp v112, v158 row_shr:1 row_mask:0xf bank_mask:0xf
	v_mov_b32_dpp v206, v158 row_shr:2 row_mask:0xf bank_mask:0xf
	v_mov_b32_dpp v113, v159 row_shr:1 row_mask:0xf bank_mask:0xf
	v_mov_b32_dpp v207, v159 row_shr:2 row_mask:0xf bank_mask:0xf
	v_mov_b32_dpp v208, v160 row_shr:1 row_mask:0xf bank_mask:0xf
	v_mov_b32_dpp v174, v160 row_shr:2 row_mask:0xf bank_mask:0xf
	v_mov_b32_dpp v209, v161 row_shr:1 row_mask:0xf bank_mask:0xf
	v_mov_b32_dpp v175, v161 row_shr:2 row_mask:0xf bank_mask:0xf
	v_mov_b32_e32 v171, 0
	v_mov_b32_e32 v172, 0
	v_mov_b32_e32 v173, 0
	s_and_saveexec_b64 s[86:87], s[78:79]
	ds_read_b128 v[170:173], v236 offset:512
	s_or_b64 exec, exec, s[86:87]
	s_waitcnt vmcnt(0)
	v_pk_fma_f32 v[174:175], v[128:129], v[174:175], v[144:145]
	v_pk_fma_f32 v[206:207], v[126:127], v[206:207], v[142:143]
	v_pk_fma_f32 v[174:175], v[136:137], v[208:209], v[174:175]
	v_pk_fma_f32 v[112:113], v[134:135], v[112:113], v[206:207]
	v_pk_fma_f32 v[206:207], v[160:161], v[132:133], v[174:175]
	v_mov_b32_e32 v199, v198
	v_mul_f32_e32 v0, 0xbfb8aa3b, v207
	v_exp_f32_e32 v0, v0
	v_mov_b32_e32 v174, v198
	v_mov_b32_e32 v175, v198
	v_pk_mul_f32 v[174:175], v[156:157], v[174:175]
	v_add_f32_e32 v0, 1.0, v0
	v_pk_mul_f32 v[208:209], v[154:155], v[198:199]
	v_pk_mul_f32 v[154:155], v[152:153], v[196:197] op_sel_hi:[1,0]
	v_pk_mul_f32 v[156:157], v[150:151], v[196:197] op_sel_hi:[1,0]
	v_pk_mul_f32 v[150:151], v[148:149], v[196:197] op_sel_hi:[1,0]
	v_pk_mul_f32 v[152:153], v[146:147], v[196:197] op_sel_hi:[1,0]
	v_pk_mul_f32 v[146:147], v[102:103], v[194:195] op_sel_hi:[1,0]
	v_pk_mul_f32 v[148:149], v[100:101], v[194:195] op_sel_hi:[1,0]
	v_pk_mul_f32 v[100:101], v[96:97], v[194:195] op_sel_hi:[1,0]
	s_waitcnt lgkmcnt(0)
	v_mov_b32_dpp v96, v170 row_ror:1 row_mask:0xf bank_mask:0xf bound_ctrl:1
	v_mov_b32_dpp v102, v170 row_ror:2 row_mask:0xf bank_mask:0xf bound_ctrl:1
	v_mov_b32_dpp v97, v171 row_ror:1 row_mask:0xf bank_mask:0xf bound_ctrl:1
	v_mov_b32_dpp v103, v171 row_ror:2 row_mask:0xf bank_mask:0xf bound_ctrl:1
	v_mov_b32_dpp v170, v172 row_ror:1 row_mask:0xf bank_mask:0xf bound_ctrl:1
	v_mov_b32_dpp v172, v172 row_ror:2 row_mask:0xf bank_mask:0xf bound_ctrl:1
	v_mov_b32_dpp v171, v173 row_ror:1 row_mask:0xf bank_mask:0xf bound_ctrl:1
	v_mov_b32_dpp v173, v173 row_ror:2 row_mask:0xf bank_mask:0xf bound_ctrl:1
	v_rcp_f32_e32 v0, v0
	v_mov_b32_dpp v172, v174 row_shr:2 row_mask:0xf bank_mask:0xf
	v_mov_b32_dpp v173, v175 row_shr:2 row_mask:0xf bank_mask:0xf
	v_mov_b32_dpp v102, v208 row_shr:2 row_mask:0xf bank_mask:0xf
	v_mov_b32_dpp v103, v209 row_shr:2 row_mask:0xf bank_mask:0xf
	v_mov_b32_dpp v170, v174 row_shr:1 row_mask:0xf bank_mask:0xf
	v_mov_b32_dpp v171, v175 row_shr:1 row_mask:0xf bank_mask:0xf
	v_pk_fma_f32 v[172:173], v[116:117], v[172:173], v[140:141]
	v_mov_b32_dpp v96, v208 row_shr:1 row_mask:0xf bank_mask:0xf
	v_mov_b32_dpp v97, v209 row_shr:1 row_mask:0xf bank_mask:0xf
	v_pk_fma_f32 v[102:103], v[114:115], v[102:103], v[138:139]
	v_pk_fma_f32 v[170:171], v[120:121], v[170:171], v[172:173]
	v_pk_fma_f32 v[96:97], v[118:119], v[96:97], v[102:103]
	v_pk_fma_f32 v[102:103], v[174:175], v[124:125], v[170:171]
	v_mul_f32_e32 v0, v207, v0
	v_mul_f32_e32 v0, v0, v103
	v_mul_f32_e32 v103, 0xbfb8aa3b, v206
	v_exp_f32_e32 v103, v103
	v_pk_fma_f32 v[112:113], v[158:159], v[130:131], v[112:113]
	v_pk_fma_f32 v[96:97], v[208:209], v[122:123], v[96:97]
	v_mov_b32_dpp v172, v174 row_ror:2 row_mask:0xf bank_mask:0xf bound_ctrl:1
	v_add_f32_e32 v103, 1.0, v103
	v_rcp_f32_e32 v103, v103
	v_mov_b32_dpp v173, v175 row_ror:2 row_mask:0xf bank_mask:0xf bound_ctrl:1
	v_mov_b32_dpp v170, v174 row_ror:1 row_mask:0xf bank_mask:0xf bound_ctrl:1
	v_mov_b32_dpp v172, v150 row_shr:2 row_mask:0xf bank_mask:0xf
	v_mul_f32_e32 v103, v206, v103
	v_mul_f32_e32 v102, v103, v102
	v_mul_f32_e32 v103, 0xbfb8aa3b, v113
	v_exp_f32_e32 v103, v103
	v_mov_b32_dpp v171, v175 row_ror:1 row_mask:0xf bank_mask:0xf bound_ctrl:1
	v_mov_b32_dpp v173, v151 row_shr:2 row_mask:0xf bank_mask:0xf
	v_mov_b32_dpp v170, v150 row_shr:1 row_mask:0xf bank_mask:0xf
	v_add_f32_e32 v103, 1.0, v103
	v_rcp_f32_e32 v103, v103
	v_mov_b32_dpp v171, v151 row_shr:1 row_mask:0xf bank_mask:0xf
	v_pk_fma_f32 v[172:173], v[116:117], v[172:173], v[140:141]
	v_pk_mul_f32 v[98:99], v[98:99], v[194:195] op_sel_hi:[1,0]
	v_mul_f32_e32 v103, v113, v103
	v_mul_f32_e32 v97, v103, v97
	v_mul_f32_e32 v103, 0xbfb8aa3b, v112
	v_exp_f32_e32 v103, v103
	v_pk_fma_f32 v[170:171], v[120:121], v[170:171], v[172:173]
; #define PG8_LAS __attribute__((address_space(3)))
; __device__ __forceinline__ unsigned cvt_pk_bf16(float lo, float hi) { unsigned r; asm volatile("v_cvt_pk_bf16_f32 %0, %1, %2" : "=v"(r) : "v"(lo), "v"(hi)); return r; }
; #define PG8_ROR(src, ctrl) __builtin_bit_cast(float, __builtin_amdgcn_mov_dpp(__builtin_bit_cast(int, (float)(src)), (ctrl), 0xf, 0xf, true))
; #define PG8_DPP(old, src, ctrl) __builtin_bit_cast(float, __builtin_amdgcn_update_dpp(__builtin_bit_cast(int, (float)(old)), __builtin_bit_cast(int, (float)(src)), (ctrl), 0xf, 0xf, false))
;     __device__ __forceinline__ void operator()(f32x4 (&acc)[2][2][4][2], const Unit& u, int wr, int wc, int fr, int fq, PG8_LAS unsigned char* lds, int wid, int lane) const {
;     ...
;                     for (int bj = 0; bj < 2; ++bj) { const f32x4 cur = acc[ai][bj][m][n]; f32x4 prev;
;                         if (m > 0) prev = acc[ai][bj][m > 0 ? m - 1 : 0][n];
;                         else { prev = (f32x4){0.f, 0.f, 0.f, 0.f}; if (b > 0 && fr >= 14) prev = *(const PG8_LAS f32x4*)(X + ((b - 1) * 2 + fr - 14) * 256 + bj * HALF + wc * 32 + 8 * fq + 4 * n); }
;                         f32x4 p1, p2;
; #pragma unroll
;                         for (int j = 0; j < 4; ++j) { const float r1 = PG8_ROR(prev[j], 0x121), r2 = PG8_ROR(prev[j], 0x122);
;                             p1[j] = PG8_DPP(r1, cur[j], 0x111); p2[j] = PG8_DPP(r2, cur[j], 0x112); }
;                         c[bj] = bs[bj] + w[bj][0] * p2 + w[bj][1] * p1 + w[bj][2] * cur; }
;                     float h4[4];
; #pragma unroll
;                     for (int j = 0; j < 4; ++j) h4[j] = c[0][j] * __builtin_amdgcn_rcpf(1.0f + __expf(-c[0][j])) * c[1][j];
;                     if (n == 0) { pk0[ai][m][0] = cvt_pk_bf16(h4[0], h4[1]); pk0[ai][m][1] = cvt_pk_bf16(h4[2], h4[3]); }
	v_add_f32_e32 v103, 1.0, v103
	v_rcp_f32_e32 v103, v103
	s_nop 0
	v_mul_f32_e32 v103, v112, v103
	v_mul_f32_e32 v96, v103, v96
	v_cvt_pk_bf16_f32 v112, v96, v97
	v_cvt_pk_bf16_f32 v113, v102, v0
	v_mov_b32_dpp v102, v158 row_ror:2 row_mask:0xf bank_mask:0xf bound_ctrl:1
	v_mov_b32_dpp v97, v159 row_ror:1 row_mask:0xf bank_mask:0xf bound_ctrl:1
	v_mov_b32_dpp v96, v158 row_ror:1 row_mask:0xf bank_mask:0xf bound_ctrl:1
	v_mov_b32_dpp v103, v159 row_ror:2 row_mask:0xf bank_mask:0xf bound_ctrl:1
	v_mov_b32_dpp v158, v160 row_ror:1 row_mask:0xf bank_mask:0xf bound_ctrl:1
	v_mov_b32_dpp v160, v160 row_ror:2 row_mask:0xf bank_mask:0xf bound_ctrl:1
	v_mov_b32_dpp v159, v161 row_ror:1 row_mask:0xf bank_mask:0xf bound_ctrl:1
	v_mov_b32_dpp v161, v161 row_ror:2 row_mask:0xf bank_mask:0xf bound_ctrl:1
	v_mov_b32_dpp v102, v156 row_shr:2 row_mask:0xf bank_mask:0xf
	v_mov_b32_dpp v103, v157 row_shr:2 row_mask:0xf bank_mask:0xf
	v_mov_b32_dpp v160, v154 row_shr:2 row_mask:0xf bank_mask:0xf
	v_mov_b32_dpp v161, v155 row_shr:2 row_mask:0xf bank_mask:0xf
	v_mov_b32_dpp v96, v156 row_shr:1 row_mask:0xf bank_mask:0xf
	v_mov_b32_dpp v97, v157 row_shr:1 row_mask:0xf bank_mask:0xf
	v_mov_b32_dpp v158, v154 row_shr:1 row_mask:0xf bank_mask:0xf
	v_mov_b32_dpp v159, v155 row_shr:1 row_mask:0xf bank_mask:0xf
	v_pk_fma_f32 v[160:161], v[128:129], v[160:161], v[144:145]
	v_pk_fma_f32 v[102:103], v[126:127], v[102:103], v[142:143]
	s_nop 0
	v_pk_fma_f32 v[96:97], v[134:135], v[96:97], v[102:103]
	v_pk_fma_f32 v[102:103], v[136:137], v[158:159], v[160:161]
	v_mov_b32_dpp v160, v208 row_ror:2 row_mask:0xf bank_mask:0xf bound_ctrl:1
	v_pk_fma_f32 v[102:103], v[154:155], v[132:133], v[102:103]
	v_mov_b32_dpp v161, v209 row_ror:2 row_mask:0xf bank_mask:0xf bound_ctrl:1
	v_mul_f32_e32 v0, 0xbfb8aa3b, v103
	v_exp_f32_e32 v0, v0
	v_mov_b32_dpp v158, v208 row_ror:1 row_mask:0xf bank_mask:0xf bound_ctrl:1
	v_mov_b32_dpp v160, v152 row_shr:2 row_mask:0xf bank_mask:0xf
	v_mov_b32_dpp v159, v209 row_ror:1 row_mask:0xf bank_mask:0xf bound_ctrl:1
	v_add_f32_e32 v0, 1.0, v0
	v_rcp_f32_e32 v0, v0
	v_mov_b32_dpp v161, v153 row_shr:2 row_mask:0xf bank_mask:0xf
	v_mov_b32_dpp v158, v152 row_shr:1 row_mask:0xf bank_mask:0xf
	v_mov_b32_dpp v159, v153 row_shr:1 row_mask:0xf bank_mask:0xf
	v_mul_f32_e32 v0, v103, v0
	v_mul_f32_e32 v103, 0xbfb8aa3b, v102
	v_exp_f32_e32 v103, v103
	v_pk_fma_f32 v[160:161], v[114:115], v[160:161], v[138:139]
	v_pk_fma_f32 v[96:97], v[156:157], v[130:131], v[96:97]
	v_pk_fma_f32 v[158:159], v[118:119], v[158:159], v[160:161]
	v_add_f32_e32 v103, 1.0, v103
	v_rcp_f32_e32 v103, v103
	v_pk_fma_f32 v[160:161], v[150:151], v[124:125], v[170:171]
	v_pk_fma_f32 v[158:159], v[152:153], v[122:123], v[158:159]
	v_mul_f32_e32 v0, v0, v161
	v_mul_f32_e32 v102, v102, v103
	v_mul_f32_e32 v103, v102, v160
	v_mul_f32_e32 v102, 0xbfb8aa3b, v97
	v_exp_f32_e32 v102, v102
	s_nop 0
	v_add_f32_e32 v102, 1.0, v102
	v_rcp_f32_e32 v102, v102
	s_nop 0
	v_mul_f32_e32 v97, v97, v102
	v_mul_f32_e32 v102, 0xbfb8aa3b, v96
	v_exp_f32_e32 v102, v102
	v_mul_f32_e32 v97, v97, v159
	v_mov_b32_dpp v159, v155 row_ror:1 row_mask:0xf bank_mask:0xf bound_ctrl:1
	v_mov_b32_dpp v155, v155 row_ror:2 row_mask:0xf bank_mask:0xf bound_ctrl:1
	v_add_f32_e32 v102, 1.0, v102
	v_rcp_f32_e32 v102, v102
	v_mov_b32_dpp v155, v147 row_shr:2 row_mask:0xf bank_mask:0xf
	v_mov_b32_dpp v159, v147 row_shr:1 row_mask:0xf bank_mask:0xf
	v_mul_f32_e32 v96, v96, v102
	v_mul_f32_e32 v96, v96, v158
	v_mov_b32_dpp v158, v154 row_ror:1 row_mask:0xf bank_mask:0xf bound_ctrl:1
	v_mov_b32_dpp v154, v154 row_ror:2 row_mask:0xf bank_mask:0xf bound_ctrl:1
	v_cvt_pk_bf16_f32 v102, v96, v97
	v_cvt_pk_bf16_f32 v103, v103, v0
	v_mov_b32_dpp v96, v156 row_ror:1 row_mask:0xf bank_mask:0xf bound_ctrl:1
	v_mov_b32_dpp v158, v146 row_shr:1 row_mask:0xf bank_mask:0xf
	v_mov_b32_dpp v154, v146 row_shr:2 row_mask:0xf bank_mask:0xf
	v_pk_fma_f32 v[154:155], v[128:129], v[154:155], v[144:145]
	v_mov_b32_dpp v156, v156 row_ror:2 row_mask:0xf bank_mask:0xf bound_ctrl:1
	v_pk_fma_f32 v[154:155], v[136:137], v[158:159], v[154:155]
	v_mov_b32_dpp v158, v150 row_ror:1 row_mask:0xf bank_mask:0xf bound_ctrl:1
	v_pk_fma_f32 v[154:155], v[146:147], v[132:133], v[154:155]
	v_mov_b32_dpp v150, v150 row_ror:2 row_mask:0xf bank_mask:0xf bound_ctrl:1
	v_mul_f32_e32 v0, 0xbfb8aa3b, v155
	v_exp_f32_e32 v0, v0
	v_mov_b32_dpp v159, v151 row_ror:1 row_mask:0xf bank_mask:0xf bound_ctrl:1
	v_mov_b32_dpp v151, v151 row_ror:2 row_mask:0xf bank_mask:0xf bound_ctrl:1
	v_mov_b32_dpp v150, v98 row_shr:2 row_mask:0xf bank_mask:0xf
	v_add_f32_e32 v0, 1.0, v0
	v_rcp_f32_e32 v0, v0
	v_mov_b32_dpp v151, v99 row_shr:2 row_mask:0xf bank_mask:0xf
	v_mov_b32_dpp v158, v98 row_shr:1 row_mask:0xf bank_mask:0xf
	v_mov_b32_dpp v159, v99 row_shr:1 row_mask:0xf bank_mask:0xf
	v_pk_fma_f32 v[150:151], v[116:117], v[150:151], v[140:141]
	v_mul_f32_e32 v0, v155, v0
	v_pk_fma_f32 v[150:151], v[120:121], v[158:159], v[150:151]
	v_mov_b32_dpp v97, v157 row_ror:1 row_mask:0xf bank_mask:0xf bound_ctrl:1
	v_pk_fma_f32 v[150:151], v[98:99], v[124:125], v[150:151]
	v_mov_b32_dpp v157, v157 row_ror:2 row_mask:0xf bank_mask:0xf bound_ctrl:1
	v_mul_f32_e32 v0, v0, v151
	v_mul_f32_e32 v151, 0xbfb8aa3b, v154
	v_exp_f32_e32 v151, v151
	v_mov_b32_dpp v156, v148 row_shr:2 row_mask:0xf bank_mask:0xf
	v_mov_b32_dpp v157, v149 row_shr:2 row_mask:0xf bank_mask:0xf
	v_mov_b32_dpp v96, v148 row_shr:1 row_mask:0xf bank_mask:0xf
	v_add_f32_e32 v151, 1.0, v151
	v_rcp_f32_e32 v151, v151
	v_mov_b32_dpp v97, v149 row_shr:1 row_mask:0xf bank_mask:0xf
	v_pk_fma_f32 v[156:157], v[126:127], v[156:157], v[142:143]
; #define PG8_LAS __attribute__((address_space(3)))
; __device__ __forceinline__ unsigned cvt_pk_bf16(float lo, float hi) { unsigned r; asm volatile("v_cvt_pk_bf16_f32 %0, %1, %2" : "=v"(r) : "v"(lo), "v"(hi)); return r; }
; #define PG8_ROR(src, ctrl) __builtin_bit_cast(float, __builtin_amdgcn_mov_dpp(__builtin_bit_cast(int, (float)(src)), (ctrl), 0xf, 0xf, true))
; #define PG8_DPP(old, src, ctrl) __builtin_bit_cast(float, __builtin_amdgcn_update_dpp(__builtin_bit_cast(int, (float)(old)), __builtin_bit_cast(int, (float)(src)), (ctrl), 0xf, 0xf, false))
;     __device__ __forceinline__ void operator()(f32x4 (&acc)[2][2][4][2], const Unit& u, int wr, int wc, int fr, int fq, PG8_LAS unsigned char* lds, int wid, int lane) const {
;     ...
;                     for (int bj = 0; bj < 2; ++bj) { const f32x4 cur = acc[ai][bj][m][n]; f32x4 prev;
;                         if (m > 0) prev = acc[ai][bj][m > 0 ? m - 1 : 0][n];
;                         else { prev = (f32x4){0.f, 0.f, 0.f, 0.f}; if (b > 0 && fr >= 14) prev = *(const PG8_LAS f32x4*)(X + ((b - 1) * 2 + fr - 14) * 256 + bj * HALF + wc * 32 + 8 * fq + 4 * n); }
;                         f32x4 p1, p2;
; #pragma unroll
;                         for (int j = 0; j < 4; ++j) { const float r1 = PG8_ROR(prev[j], 0x121), r2 = PG8_ROR(prev[j], 0x122);
;                             p1[j] = PG8_DPP(r1, cur[j], 0x111); p2[j] = PG8_DPP(r2, cur[j], 0x112); }
;                         c[bj] = bs[bj] + w[bj][0] * p2 + w[bj][1] * p1 + w[bj][2] * cur; }
;                     float h4[4];
; #pragma unroll
;                     for (int j = 0; j < 4; ++j) h4[j] = c[0][j] * __builtin_amdgcn_rcpf(1.0f + __expf(-c[0][j])) * c[1][j];
;                     if (n == 0) { pk0[ai][m][0] = cvt_pk_bf16(h4[0], h4[1]); pk0[ai][m][1] = cvt_pk_bf16(h4[2], h4[3]); }
;                     else { u32x4 pk; pk.x = pk0[ai][m][0]; pk.y = pk0[ai][m][1]; pk.z = cvt_pk_bf16(h4[0], h4[1]); pk.w = cvt_pk_bf16(h4[2], h4[3]);
	v_mul_f32_e32 v151, v154, v151
	v_pk_fma_f32 v[96:97], v[134:135], v[96:97], v[156:157]
	v_mul_f32_e32 v150, v151, v150
	v_pk_fma_f32 v[96:97], v[148:149], v[130:131], v[96:97]
	v_mov_b32_dpp v156, v152 row_ror:1 row_mask:0xf bank_mask:0xf bound_ctrl:1
	v_mul_f32_e32 v151, 0xbfb8aa3b, v97
	v_exp_f32_e32 v151, v151
	v_mov_b32_dpp v152, v152 row_ror:2 row_mask:0xf bank_mask:0xf bound_ctrl:1
	v_mov_b32_dpp v157, v153 row_ror:1 row_mask:0xf bank_mask:0xf bound_ctrl:1
	v_mov_b32_dpp v153, v153 row_ror:2 row_mask:0xf bank_mask:0xf bound_ctrl:1
	v_add_f32_e32 v151, 1.0, v151
	v_rcp_f32_e32 v151, v151
	v_mov_b32_dpp v152, v100 row_shr:2 row_mask:0xf bank_mask:0xf
	v_mov_b32_dpp v153, v101 row_shr:2 row_mask:0xf bank_mask:0xf
	v_mov_b32_dpp v156, v100 row_shr:1 row_mask:0xf bank_mask:0xf
	v_mul_f32_e32 v97, v97, v151
	v_mul_f32_e32 v151, 0xbfb8aa3b, v96
	v_exp_f32_e32 v151, v151
	v_mov_b32_dpp v157, v101 row_shr:1 row_mask:0xf bank_mask:0xf
	v_pk_fma_f32 v[152:153], v[114:115], v[152:153], v[138:139]
	v_add_f32_e32 v151, 1.0, v151
	v_rcp_f32_e32 v151, v151
	v_pk_fma_f32 v[152:153], v[118:119], v[156:157], v[152:153]
	v_mul_f32_e32 v96, v96, v151
	v_pk_fma_f32 v[152:153], v[100:101], v[122:123], v[152:153]
	v_mov_b32_dpp v151, v149 row_ror:1 row_mask:0xf bank_mask:0xf bound_ctrl:1
	v_mul_f32_e32 v97, v97, v153
	v_mul_f32_e32 v96, v96, v152
	v_mov_b32_dpp v152, v146 row_ror:1 row_mask:0xf bank_mask:0xf bound_ctrl:1
	v_mov_b32_dpp v146, v146 row_ror:2 row_mask:0xf bank_mask:0xf bound_ctrl:1
	v_mov_b32_dpp v153, v147 row_ror:1 row_mask:0xf bank_mask:0xf bound_ctrl:1
	v_mov_b32_dpp v147, v147 row_ror:2 row_mask:0xf bank_mask:0xf bound_ctrl:1
	v_mov_b32_dpp v146, v168 row_shr:2 row_mask:0xf bank_mask:0xf
	v_mov_b32_dpp v152, v168 row_shr:1 row_mask:0xf bank_mask:0xf
	v_mov_b32_dpp v147, v169 row_shr:2 row_mask:0xf bank_mask:0xf
	v_mov_b32_dpp v153, v169 row_shr:1 row_mask:0xf bank_mask:0xf
	v_pk_fma_f32 v[146:147], v[128:129], v[146:147], v[144:145]
	v_cvt_pk_bf16_f32 v96, v96, v97
	v_cvt_pk_bf16_f32 v97, v150, v0
	v_mov_b32_dpp v150, v148 row_ror:1 row_mask:0xf bank_mask:0xf bound_ctrl:1
	v_pk_fma_f32 v[146:147], v[136:137], v[152:153], v[146:147]
	v_mov_b32_dpp v152, v98 row_ror:1 row_mask:0xf bank_mask:0xf bound_ctrl:1
	v_pk_fma_f32 v[146:147], v[168:169], v[132:133], v[146:147]
	v_mov_b32_dpp v98, v98 row_ror:2 row_mask:0xf bank_mask:0xf bound_ctrl:1
	v_mul_f32_e32 v0, 0xbfb8aa3b, v147
	v_exp_f32_e32 v0, v0
	v_mov_b32_dpp v153, v99 row_ror:1 row_mask:0xf bank_mask:0xf bound_ctrl:1
	v_mov_b32_dpp v99, v99 row_ror:2 row_mask:0xf bank_mask:0xf bound_ctrl:1
	v_mov_b32_dpp v98, v164 row_shr:2 row_mask:0xf bank_mask:0xf
	v_add_f32_e32 v0, 1.0, v0
	v_rcp_f32_e32 v0, v0
	v_mov_b32_dpp v99, v165 row_shr:2 row_mask:0xf bank_mask:0xf
	v_mov_b32_dpp v152, v164 row_shr:1 row_mask:0xf bank_mask:0xf
	v_mov_b32_dpp v153, v165 row_shr:1 row_mask:0xf bank_mask:0xf
	v_pk_fma_f32 v[98:99], v[116:117], v[98:99], v[140:141]
	v_mul_f32_e32 v0, v147, v0
	v_pk_fma_f32 v[98:99], v[120:121], v[152:153], v[98:99]
	v_mov_b32_dpp v148, v148 row_ror:2 row_mask:0xf bank_mask:0xf bound_ctrl:1
	v_pk_fma_f32 v[98:99], v[164:165], v[124:125], v[98:99]
	v_mov_b32_dpp v149, v149 row_ror:2 row_mask:0xf bank_mask:0xf bound_ctrl:1
	v_mul_f32_e32 v0, v0, v99
	v_mul_f32_e32 v99, 0xbfb8aa3b, v146
	v_exp_f32_e32 v99, v99
	v_mov_b32_dpp v148, v166 row_shr:2 row_mask:0xf bank_mask:0xf
	v_mov_b32_dpp v149, v167 row_shr:2 row_mask:0xf bank_mask:0xf
	v_mov_b32_dpp v150, v166 row_shr:1 row_mask:0xf bank_mask:0xf
	v_add_f32_e32 v99, 1.0, v99
	v_rcp_f32_e32 v99, v99
	v_mov_b32_dpp v151, v167 row_shr:1 row_mask:0xf bank_mask:0xf
	v_pk_fma_f32 v[148:149], v[126:127], v[148:149], v[142:143]
	v_mul_f32_e32 v99, v146, v99
	v_pk_fma_f32 v[148:149], v[134:135], v[150:151], v[148:149]
	v_mul_f32_e32 v98, v99, v98
	v_pk_fma_f32 v[148:149], v[166:167], v[130:131], v[148:149]
	v_mov_b32_dpp v150, v100 row_ror:1 row_mask:0xf bank_mask:0xf bound_ctrl:1
	v_mul_f32_e32 v99, 0xbfb8aa3b, v149
	v_exp_f32_e32 v99, v99
	v_mov_b32_dpp v100, v100 row_ror:2 row_mask:0xf bank_mask:0xf bound_ctrl:1
	v_mov_b32_dpp v151, v101 row_ror:1 row_mask:0xf bank_mask:0xf bound_ctrl:1
	v_mov_b32_dpp v101, v101 row_ror:2 row_mask:0xf bank_mask:0xf bound_ctrl:1
	v_add_f32_e32 v99, 1.0, v99
	v_rcp_f32_e32 v99, v99
	v_mov_b32_dpp v100, v162 row_shr:2 row_mask:0xf bank_mask:0xf
	v_mov_b32_dpp v101, v163 row_shr:2 row_mask:0xf bank_mask:0xf
	v_mov_b32_dpp v150, v162 row_shr:1 row_mask:0xf bank_mask:0xf
	v_mov_b32_dpp v151, v163 row_shr:1 row_mask:0xf bank_mask:0xf
	v_pk_fma_f32 v[100:101], v[114:115], v[100:101], v[138:139]
	v_mul_f32_e32 v99, v149, v99
	v_pk_fma_f32 v[100:101], v[118:119], v[150:151], v[100:101]
	v_mov_b32_e32 v146, 0
	v_pk_fma_f32 v[100:101], v[162:163], v[122:123], v[100:101]
	v_mov_b32_e32 v149, 0
	v_mul_f32_e32 v99, v99, v101
	v_mul_f32_e32 v101, 0xbfb8aa3b, v148
	v_exp_f32_e32 v101, v101
	v_mov_b32_e32 v150, 0
	v_mov_b32_e32 v151, 0
	v_add_f32_e32 v101, 1.0, v101
	v_rcp_f32_e32 v101, v101
	s_nop 0
	v_mul_f32_e32 v101, v148, v101
	v_mul_f32_e32 v100, v101, v100
	v_mov_b32_e32 v148, 0
	v_cvt_pk_bf16_f32 v100, v100, v99
	v_cvt_pk_bf16_f32 v101, v98, v0
	s_and_saveexec_b64 s[86:87], s[80:81]
	ds_read_b128 v[148:151], v237
	s_or_b64 exec, exec, s[86:87]
	v_pk_mul_f32 v[94:95], v[94:95], v[192:193] op_sel_hi:[1,0]
	v_pk_mul_f32 v[98:99], v[92:93], v[192:193] op_sel_hi:[1,0]
	s_waitcnt lgkmcnt(0)
; #define PG8_LAS __attribute__((address_space(3)))
; __device__ __forceinline__ unsigned cvt_pk_bf16(float lo, float hi) { unsigned r; asm volatile("v_cvt_pk_bf16_f32 %0, %1, %2" : "=v"(r) : "v"(lo), "v"(hi)); return r; }
; #define PG8_ROR(src, ctrl) __builtin_bit_cast(float, __builtin_amdgcn_mov_dpp(__builtin_bit_cast(int, (float)(src)), (ctrl), 0xf, 0xf, true))
; #define PG8_DPP(old, src, ctrl) __builtin_bit_cast(float, __builtin_amdgcn_update_dpp(__builtin_bit_cast(int, (float)(old)), __builtin_bit_cast(int, (float)(src)), (ctrl), 0xf, 0xf, false))
;     __device__ __forceinline__ void operator()(f32x4 (&acc)[2][2][4][2], const Unit& u, int wr, int wc, int fr, int fq, PG8_LAS unsigned char* lds, int wid, int lane) const {
;     ...
;             for (int m = 0; m < 4; ++m) { const float rs = tbl[ai * HALF + wr * 64 + m * 16 + fr];
; #pragma unroll
;                 for (int bj = 0; bj < 2; ++bj)
; #pragma unroll
;                     for (int n = 0; n < 2; ++n) acc[ai][bj][m][n] = acc[ai][bj][m][n] * rs; }
;     ...
;                     for (int bj = 0; bj < 2; ++bj) { const f32x4 cur = acc[ai][bj][m][n]; f32x4 prev;
;                         if (m > 0) prev = acc[ai][bj][m > 0 ? m - 1 : 0][n];
;                         else { prev = (f32x4){0.f, 0.f, 0.f, 0.f}; if (b > 0 && fr >= 14) prev = *(const PG8_LAS f32x4*)(X + ((b - 1) * 2 + fr - 14) * 256 + bj * HALF + wc * 32 + 8 * fq + 4 * n); }
;                         f32x4 p1, p2;
; #pragma unroll
;                         for (int j = 0; j < 4; ++j) { const float r1 = PG8_ROR(prev[j], 0x121), r2 = PG8_ROR(prev[j], 0x122);
;                             p1[j] = PG8_DPP(r1, cur[j], 0x111); p2[j] = PG8_DPP(r2, cur[j], 0x112); }
;                         c[bj] = bs[bj] + w[bj][0] * p2 + w[bj][1] * p1 + w[bj][2] * cur; }
;                     float h4[4];
; #pragma unroll
;                     for (int j = 0; j < 4; ++j) h4[j] = c[0][j] * __builtin_amdgcn_rcpf(1.0f + __expf(-c[0][j])) * c[1][j];
;                     if (n == 0) { pk0[ai][m][0] = cvt_pk_bf16(h4[0], h4[1]); pk0[ai][m][1] = cvt_pk_bf16(h4[2], h4[3]); }
	v_mov_b32_dpp v92, v148 row_ror:1 row_mask:0xf bank_mask:0xf bound_ctrl:1
	v_mov_b32_dpp v152, v148 row_ror:2 row_mask:0xf bank_mask:0xf bound_ctrl:1
	v_mov_b32_dpp v93, v149 row_ror:1 row_mask:0xf bank_mask:0xf bound_ctrl:1
	v_mov_b32_dpp v153, v149 row_ror:2 row_mask:0xf bank_mask:0xf bound_ctrl:1
	v_mov_b32_dpp v154, v150 row_ror:1 row_mask:0xf bank_mask:0xf bound_ctrl:1
	v_mov_b32_dpp v150, v150 row_ror:2 row_mask:0xf bank_mask:0xf bound_ctrl:1
	v_mov_b32_dpp v155, v151 row_ror:1 row_mask:0xf bank_mask:0xf bound_ctrl:1
	v_mov_b32_dpp v151, v151 row_ror:2 row_mask:0xf bank_mask:0xf bound_ctrl:1
	v_mov_b32_dpp v92, v98 row_shr:1 row_mask:0xf bank_mask:0xf
	v_mov_b32_dpp v152, v98 row_shr:2 row_mask:0xf bank_mask:0xf
	v_mov_b32_dpp v93, v99 row_shr:1 row_mask:0xf bank_mask:0xf
	v_mov_b32_dpp v153, v99 row_shr:2 row_mask:0xf bank_mask:0xf
	v_mov_b32_dpp v154, v94 row_shr:1 row_mask:0xf bank_mask:0xf
	v_mov_b32_dpp v150, v94 row_shr:2 row_mask:0xf bank_mask:0xf
	v_mov_b32_dpp v155, v95 row_shr:1 row_mask:0xf bank_mask:0xf
	v_mov_b32_dpp v151, v95 row_shr:2 row_mask:0xf bank_mask:0xf
	v_mov_b32_e32 v147, 0
	v_mov_b32_e32 v148, 0
	v_mov_b32_e32 v149, 0
	s_and_saveexec_b64 s[86:87], s[80:81]
	ds_read_b128 v[146:149], v237 offset:512
	s_or_b64 exec, exec, s[86:87]
	v_pk_fma_f32 v[150:151], v[128:129], v[150:151], v[144:145]
	v_pk_fma_f32 v[152:153], v[126:127], v[152:153], v[142:143]
	v_pk_fma_f32 v[150:151], v[136:137], v[154:155], v[150:151]
	v_pk_fma_f32 v[92:93], v[134:135], v[92:93], v[152:153]
	v_pk_fma_f32 v[152:153], v[94:95], v[132:133], v[150:151]
	v_pk_fma_f32 v[154:155], v[98:99], v[130:131], v[92:93]
	v_mul_f32_e32 v0, 0xbfb8aa3b, v153
	v_exp_f32_e32 v0, v0
	v_mov_b32_e32 v92, v192
	v_mov_b32_e32 v93, v192
	v_mov_b32_e32 v193, v192
	v_add_f32_e32 v0, 1.0, v0
	v_pk_mul_f32 v[150:151], v[90:91], v[92:93]
	v_pk_mul_f32 v[90:91], v[86:87], v[190:191] op_sel_hi:[1,0]
	v_pk_mul_f32 v[92:93], v[84:85], v[190:191] op_sel_hi:[1,0]
	v_pk_mul_f32 v[86:87], v[82:83], v[190:191] op_sel_hi:[1,0]
	v_pk_mul_f32 v[82:83], v[78:79], v[188:189] op_sel_hi:[1,0]
	v_pk_mul_f32 v[84:85], v[76:77], v[188:189] op_sel_hi:[1,0]
	v_pk_mul_f32 v[76:77], v[72:73], v[188:189] op_sel_hi:[1,0]
	s_waitcnt lgkmcnt(0)
	v_mov_b32_dpp v72, v146 row_ror:1 row_mask:0xf bank_mask:0xf bound_ctrl:1
	v_mov_b32_dpp v78, v146 row_ror:2 row_mask:0xf bank_mask:0xf bound_ctrl:1
	v_mov_b32_dpp v73, v147 row_ror:1 row_mask:0xf bank_mask:0xf bound_ctrl:1
	v_mov_b32_dpp v79, v147 row_ror:2 row_mask:0xf bank_mask:0xf bound_ctrl:1
	v_mov_b32_dpp v146, v148 row_ror:2 row_mask:0xf bank_mask:0xf bound_ctrl:1
	v_mov_b32_dpp v147, v149 row_ror:2 row_mask:0xf bank_mask:0xf bound_ctrl:1
	v_rcp_f32_e32 v0, v0
	v_pk_mul_f32 v[156:157], v[88:89], v[192:193]
	v_pk_mul_f32 v[88:89], v[80:81], v[190:191] op_sel_hi:[1,0]
	v_mov_b32_dpp v80, v148 row_ror:1 row_mask:0xf bank_mask:0xf bound_ctrl:1
	v_mov_b32_dpp v146, v150 row_shr:2 row_mask:0xf bank_mask:0xf
	v_mov_b32_dpp v81, v149 row_ror:1 row_mask:0xf bank_mask:0xf bound_ctrl:1
	v_mov_b32_dpp v147, v151 row_shr:2 row_mask:0xf bank_mask:0xf
	v_mov_b32_dpp v78, v156 row_shr:2 row_mask:0xf bank_mask:0xf
	v_mov_b32_dpp v79, v157 row_shr:2 row_mask:0xf bank_mask:0xf
	v_mov_b32_dpp v80, v150 row_shr:1 row_mask:0xf bank_mask:0xf
	v_mov_b32_dpp v81, v151 row_shr:1 row_mask:0xf bank_mask:0xf
	v_pk_fma_f32 v[146:147], v[116:117], v[146:147], v[140:141]
	v_mov_b32_dpp v72, v156 row_shr:1 row_mask:0xf bank_mask:0xf
	v_mov_b32_dpp v73, v157 row_shr:1 row_mask:0xf bank_mask:0xf
	v_pk_fma_f32 v[78:79], v[114:115], v[78:79], v[138:139]
	v_pk_fma_f32 v[80:81], v[120:121], v[80:81], v[146:147]
	v_pk_fma_f32 v[72:73], v[118:119], v[72:73], v[78:79]
	v_pk_fma_f32 v[78:79], v[150:151], v[124:125], v[80:81]
	v_mul_f32_e32 v0, v153, v0
	v_mul_f32_e32 v0, v0, v79
	v_mul_f32_e32 v79, 0xbfb8aa3b, v152
	v_exp_f32_e32 v79, v79
	v_pk_fma_f32 v[72:73], v[156:157], v[122:123], v[72:73]
	v_mov_b32_dpp v148, v150 row_ror:2 row_mask:0xf bank_mask:0xf bound_ctrl:1
	v_mov_b32_dpp v149, v151 row_ror:2 row_mask:0xf bank_mask:0xf bound_ctrl:1
	v_add_f32_e32 v79, 1.0, v79
	v_rcp_f32_e32 v79, v79
	v_mov_b32_dpp v146, v150 row_ror:1 row_mask:0xf bank_mask:0xf bound_ctrl:1
	v_mov_b32_dpp v148, v86 row_shr:2 row_mask:0xf bank_mask:0xf
	v_mov_b32_dpp v147, v151 row_ror:1 row_mask:0xf bank_mask:0xf bound_ctrl:1
	v_mul_f32_e32 v79, v152, v79
	v_mul_f32_e32 v78, v79, v78
	v_mul_f32_e32 v79, 0xbfb8aa3b, v155
	v_exp_f32_e32 v79, v79
	v_mov_b32_dpp v149, v87 row_shr:2 row_mask:0xf bank_mask:0xf
	v_mov_b32_dpp v146, v86 row_shr:1 row_mask:0xf bank_mask:0xf
	v_mov_b32_dpp v147, v87 row_shr:1 row_mask:0xf bank_mask:0xf
	v_add_f32_e32 v79, 1.0, v79
	v_rcp_f32_e32 v79, v79
	v_pk_fma_f32 v[148:149], v[116:117], v[148:149], v[140:141]
	v_pk_mul_f32 v[74:75], v[74:75], v[188:189] op_sel_hi:[1,0]
	v_pk_fma_f32 v[146:147], v[120:121], v[146:147], v[148:149]
	v_mul_f32_e32 v79, v155, v79
	v_mul_f32_e32 v73, v79, v73
	v_mul_f32_e32 v79, 0xbfb8aa3b, v154
	v_exp_f32_e32 v79, v79
	s_mov_b32 s1, 0xa000
	v_add_f32_e32 v79, 1.0, v79
	v_rcp_f32_e32 v79, v79
	s_nop 0
	v_mul_f32_e32 v79, v154, v79
	v_mul_f32_e32 v72, v79, v72
	v_cvt_pk_bf16_f32 v80, v72, v73
	v_cvt_pk_bf16_f32 v81, v78, v0
	v_mov_b32_dpp v78, v98 row_ror:2 row_mask:0xf bank_mask:0xf bound_ctrl:1
	v_mov_b32_dpp v73, v99 row_ror:1 row_mask:0xf bank_mask:0xf bound_ctrl:1
	v_mov_b32_dpp v72, v98 row_ror:1 row_mask:0xf bank_mask:0xf bound_ctrl:1
	v_mov_b32_dpp v79, v99 row_ror:2 row_mask:0xf bank_mask:0xf bound_ctrl:1
	v_mov_b32_dpp v98, v94 row_ror:1 row_mask:0xf bank_mask:0xf bound_ctrl:1
	v_mov_b32_dpp v94, v94 row_ror:2 row_mask:0xf bank_mask:0xf bound_ctrl:1
; #define PG8_LAS __attribute__((address_space(3)))
; __device__ __forceinline__ unsigned cvt_pk_bf16(float lo, float hi) { unsigned r; asm volatile("v_cvt_pk_bf16_f32 %0, %1, %2" : "=v"(r) : "v"(lo), "v"(hi)); return r; }
; #define PG8_ROR(src, ctrl) __builtin_bit_cast(float, __builtin_amdgcn_mov_dpp(__builtin_bit_cast(int, (float)(src)), (ctrl), 0xf, 0xf, true))
; #define PG8_DPP(old, src, ctrl) __builtin_bit_cast(float, __builtin_amdgcn_update_dpp(__builtin_bit_cast(int, (float)(old)), __builtin_bit_cast(int, (float)(src)), (ctrl), 0xf, 0xf, false))
;     __device__ __forceinline__ void operator()(f32x4 (&acc)[2][2][4][2], const Unit& u, int wr, int wc, int fr, int fq, PG8_LAS unsigned char* lds, int wid, int lane) const {
;     ...
;                     for (int bj = 0; bj < 2; ++bj) { const f32x4 cur = acc[ai][bj][m][n]; f32x4 prev;
;                         if (m > 0) prev = acc[ai][bj][m > 0 ? m - 1 : 0][n];
;                         else { prev = (f32x4){0.f, 0.f, 0.f, 0.f}; if (b > 0 && fr >= 14) prev = *(const PG8_LAS f32x4*)(X + ((b - 1) * 2 + fr - 14) * 256 + bj * HALF + wc * 32 + 8 * fq + 4 * n); }
;                         f32x4 p1, p2;
; #pragma unroll
;                         for (int j = 0; j < 4; ++j) { const float r1 = PG8_ROR(prev[j], 0x121), r2 = PG8_ROR(prev[j], 0x122);
;                             p1[j] = PG8_DPP(r1, cur[j], 0x111); p2[j] = PG8_DPP(r2, cur[j], 0x112); }
;                         c[bj] = bs[bj] + w[bj][0] * p2 + w[bj][1] * p1 + w[bj][2] * cur; }
;                     float h4[4];
; #pragma unroll
;                     for (int j = 0; j < 4; ++j) h4[j] = c[0][j] * __builtin_amdgcn_rcpf(1.0f + __expf(-c[0][j])) * c[1][j];
;                     if (n == 0) { pk0[ai][m][0] = cvt_pk_bf16(h4[0], h4[1]); pk0[ai][m][1] = cvt_pk_bf16(h4[2], h4[3]); }
	v_mov_b32_dpp v99, v95 row_ror:1 row_mask:0xf bank_mask:0xf bound_ctrl:1
	v_mov_b32_dpp v95, v95 row_ror:2 row_mask:0xf bank_mask:0xf bound_ctrl:1
	v_mov_b32_dpp v78, v92 row_shr:2 row_mask:0xf bank_mask:0xf
	v_mov_b32_dpp v79, v93 row_shr:2 row_mask:0xf bank_mask:0xf
	v_mov_b32_dpp v94, v90 row_shr:2 row_mask:0xf bank_mask:0xf
	v_mov_b32_dpp v95, v91 row_shr:2 row_mask:0xf bank_mask:0xf
	v_mov_b32_dpp v72, v92 row_shr:1 row_mask:0xf bank_mask:0xf
	v_mov_b32_dpp v73, v93 row_shr:1 row_mask:0xf bank_mask:0xf
	v_mov_b32_dpp v98, v90 row_shr:1 row_mask:0xf bank_mask:0xf
	v_mov_b32_dpp v99, v91 row_shr:1 row_mask:0xf bank_mask:0xf
	v_pk_fma_f32 v[94:95], v[128:129], v[94:95], v[144:145]
	v_pk_fma_f32 v[78:79], v[126:127], v[78:79], v[142:143]
	s_nop 0
	v_pk_fma_f32 v[72:73], v[134:135], v[72:73], v[78:79]
	v_pk_fma_f32 v[78:79], v[136:137], v[98:99], v[94:95]
	v_mov_b32_dpp v98, v156 row_ror:2 row_mask:0xf bank_mask:0xf bound_ctrl:1
	v_pk_fma_f32 v[78:79], v[90:91], v[132:133], v[78:79]
	v_mov_b32_dpp v99, v157 row_ror:2 row_mask:0xf bank_mask:0xf bound_ctrl:1
	v_mul_f32_e32 v0, 0xbfb8aa3b, v79
	v_exp_f32_e32 v0, v0
	v_mov_b32_dpp v94, v156 row_ror:1 row_mask:0xf bank_mask:0xf bound_ctrl:1
	v_mov_b32_dpp v98, v88 row_shr:2 row_mask:0xf bank_mask:0xf
	v_mov_b32_dpp v95, v157 row_ror:1 row_mask:0xf bank_mask:0xf bound_ctrl:1
	v_add_f32_e32 v0, 1.0, v0
	v_rcp_f32_e32 v0, v0
	v_mov_b32_dpp v99, v89 row_shr:2 row_mask:0xf bank_mask:0xf
	v_mov_b32_dpp v94, v88 row_shr:1 row_mask:0xf bank_mask:0xf
	v_mov_b32_dpp v95, v89 row_shr:1 row_mask:0xf bank_mask:0xf
	v_mul_f32_e32 v0, v79, v0
	v_mul_f32_e32 v79, 0xbfb8aa3b, v78
	v_exp_f32_e32 v79, v79
	v_pk_fma_f32 v[98:99], v[114:115], v[98:99], v[138:139]
	v_pk_fma_f32 v[72:73], v[92:93], v[130:131], v[72:73]
	v_pk_fma_f32 v[94:95], v[118:119], v[94:95], v[98:99]
	v_add_f32_e32 v79, 1.0, v79
	v_rcp_f32_e32 v79, v79
	v_pk_fma_f32 v[98:99], v[86:87], v[124:125], v[146:147]
	v_pk_fma_f32 v[94:95], v[88:89], v[122:123], v[94:95]
	v_mul_f32_e32 v0, v0, v99
	v_mul_f32_e32 v78, v78, v79
	v_mul_f32_e32 v79, v78, v98
	v_mul_f32_e32 v78, 0xbfb8aa3b, v73
	v_exp_f32_e32 v78, v78
	s_nop 0
	v_add_f32_e32 v78, 1.0, v78
	v_rcp_f32_e32 v78, v78
	s_nop 0
	v_mul_f32_e32 v73, v73, v78
	v_mul_f32_e32 v78, 0xbfb8aa3b, v72
	v_exp_f32_e32 v78, v78
	v_mul_f32_e32 v73, v73, v95
	v_mov_b32_dpp v95, v91 row_ror:1 row_mask:0xf bank_mask:0xf bound_ctrl:1
	v_mov_b32_dpp v91, v91 row_ror:2 row_mask:0xf bank_mask:0xf bound_ctrl:1
	v_add_f32_e32 v78, 1.0, v78
	v_rcp_f32_e32 v78, v78
	v_mov_b32_dpp v91, v83 row_shr:2 row_mask:0xf bank_mask:0xf
	v_mov_b32_dpp v95, v83 row_shr:1 row_mask:0xf bank_mask:0xf
	v_mul_f32_e32 v72, v72, v78
	v_mul_f32_e32 v72, v72, v94
	v_mov_b32_dpp v94, v90 row_ror:1 row_mask:0xf bank_mask:0xf bound_ctrl:1
	v_mov_b32_dpp v90, v90 row_ror:2 row_mask:0xf bank_mask:0xf bound_ctrl:1
	v_cvt_pk_bf16_f32 v78, v72, v73
	v_cvt_pk_bf16_f32 v79, v79, v0
	v_mov_b32_dpp v72, v92 row_ror:1 row_mask:0xf bank_mask:0xf bound_ctrl:1
	v_mov_b32_dpp v94, v82 row_shr:1 row_mask:0xf bank_mask:0xf
	v_mov_b32_dpp v90, v82 row_shr:2 row_mask:0xf bank_mask:0xf
	v_pk_fma_f32 v[90:91], v[128:129], v[90:91], v[144:145]
	v_mov_b32_dpp v92, v92 row_ror:2 row_mask:0xf bank_mask:0xf bound_ctrl:1
	v_pk_fma_f32 v[90:91], v[136:137], v[94:95], v[90:91]
	v_mov_b32_dpp v94, v86 row_ror:1 row_mask:0xf bank_mask:0xf bound_ctrl:1
	v_pk_fma_f32 v[90:91], v[82:83], v[132:133], v[90:91]
	v_mov_b32_dpp v86, v86 row_ror:2 row_mask:0xf bank_mask:0xf bound_ctrl:1
	v_mul_f32_e32 v0, 0xbfb8aa3b, v91
	v_exp_f32_e32 v0, v0
	v_mov_b32_dpp v95, v87 row_ror:1 row_mask:0xf bank_mask:0xf bound_ctrl:1
	v_mov_b32_dpp v87, v87 row_ror:2 row_mask:0xf bank_mask:0xf bound_ctrl:1
	v_mov_b32_dpp v86, v74 row_shr:2 row_mask:0xf bank_mask:0xf
	v_add_f32_e32 v0, 1.0, v0
	v_rcp_f32_e32 v0, v0
	v_mov_b32_dpp v87, v75 row_shr:2 row_mask:0xf bank_mask:0xf
	v_mov_b32_dpp v94, v74 row_shr:1 row_mask:0xf bank_mask:0xf
	v_mov_b32_dpp v95, v75 row_shr:1 row_mask:0xf bank_mask:0xf
	v_pk_fma_f32 v[86:87], v[116:117], v[86:87], v[140:141]
	v_mul_f32_e32 v0, v91, v0
	v_pk_fma_f32 v[86:87], v[120:121], v[94:95], v[86:87]
	v_mov_b32_dpp v73, v93 row_ror:1 row_mask:0xf bank_mask:0xf bound_ctrl:1
	v_pk_fma_f32 v[86:87], v[74:75], v[124:125], v[86:87]
	v_mov_b32_dpp v93, v93 row_ror:2 row_mask:0xf bank_mask:0xf bound_ctrl:1
	v_mul_f32_e32 v0, v0, v87
	v_mul_f32_e32 v87, 0xbfb8aa3b, v90
	v_exp_f32_e32 v87, v87
	v_mov_b32_dpp v92, v84 row_shr:2 row_mask:0xf bank_mask:0xf
	v_mov_b32_dpp v93, v85 row_shr:2 row_mask:0xf bank_mask:0xf
	v_mov_b32_dpp v72, v84 row_shr:1 row_mask:0xf bank_mask:0xf
	v_add_f32_e32 v87, 1.0, v87
	v_rcp_f32_e32 v87, v87
	v_mov_b32_dpp v73, v85 row_shr:1 row_mask:0xf bank_mask:0xf
	v_pk_fma_f32 v[92:93], v[126:127], v[92:93], v[142:143]
	v_mul_f32_e32 v87, v90, v87
	v_pk_fma_f32 v[72:73], v[134:135], v[72:73], v[92:93]
	v_mul_f32_e32 v86, v87, v86
	v_pk_fma_f32 v[72:73], v[84:85], v[130:131], v[72:73]
	v_mov_b32_dpp v92, v88 row_ror:1 row_mask:0xf bank_mask:0xf bound_ctrl:1
	v_mul_f32_e32 v87, 0xbfb8aa3b, v73
	v_exp_f32_e32 v87, v87
	v_mov_b32_dpp v88, v88 row_ror:2 row_mask:0xf bank_mask:0xf bound_ctrl:1
	v_mov_b32_dpp v93, v89 row_ror:1 row_mask:0xf bank_mask:0xf bound_ctrl:1
	v_mov_b32_dpp v89, v89 row_ror:2 row_mask:0xf bank_mask:0xf bound_ctrl:1
	v_add_f32_e32 v87, 1.0, v87
	v_rcp_f32_e32 v87, v87
	v_mov_b32_dpp v88, v76 row_shr:2 row_mask:0xf bank_mask:0xf
	v_mov_b32_dpp v89, v77 row_shr:2 row_mask:0xf bank_mask:0xf
	v_mov_b32_dpp v92, v76 row_shr:1 row_mask:0xf bank_mask:0xf
	v_mul_f32_e32 v73, v73, v87
	v_mul_f32_e32 v87, 0xbfb8aa3b, v72
	v_exp_f32_e32 v87, v87
; #define PG8_LAS __attribute__((address_space(3)))
;     __device__ __forceinline__ void operator()(f32x4 (&acc)[2][2][4][2], const Unit& u, int wr, int wc, int fr, int fq, PG8_LAS unsigned char* lds, int wid, int lane) const {
;     ...
;                 for (int k = 0; k < 3; ++k) w[bj][k] = *(const f32x4*)(cw + k * 11008 + bj * 5504 + j0 + 4 * n);
;                 bs[bj] = *(const f32x4*)(cb + bj * 5504 + j0 + 4 * n); }
;     ...
;                     for (int bj = 0; bj < 2; ++bj) { const f32x4 cur = acc[ai][bj][m][n]; f32x4 prev;
;                         if (m > 0) prev = acc[ai][bj][m > 0 ? m - 1 : 0][n];
;                         else { prev = (f32x4){0.f, 0.f, 0.f, 0.f}; if (b > 0 && fr >= 14) prev = *(const PG8_LAS f32x4*)(X + ((b - 1) * 2 + fr - 14) * 256 + bj * HALF + wc * 32 + 8 * fq + 4 * n); }
	v_mov_b32_dpp v93, v77 row_shr:1 row_mask:0xf bank_mask:0xf
	v_pk_fma_f32 v[88:89], v[114:115], v[88:89], v[138:139]
	v_add_f32_e32 v87, 1.0, v87
	v_rcp_f32_e32 v87, v87
	v_pk_fma_f32 v[88:89], v[118:119], v[92:93], v[88:89]
	v_mul_f32_e32 v72, v72, v87
	v_pk_fma_f32 v[88:89], v[76:77], v[122:123], v[88:89]
	v_mov_b32_dpp v87, v85 row_ror:1 row_mask:0xf bank_mask:0xf bound_ctrl:1
	v_mul_f32_e32 v73, v73, v89
	v_mul_f32_e32 v72, v72, v88
	v_mov_b32_dpp v88, v82 row_ror:1 row_mask:0xf bank_mask:0xf bound_ctrl:1
	v_mov_b32_dpp v82, v82 row_ror:2 row_mask:0xf bank_mask:0xf bound_ctrl:1
	v_mov_b32_dpp v89, v83 row_ror:1 row_mask:0xf bank_mask:0xf bound_ctrl:1
	v_mov_b32_dpp v83, v83 row_ror:2 row_mask:0xf bank_mask:0xf bound_ctrl:1
	v_mov_b32_dpp v82, v110 row_shr:2 row_mask:0xf bank_mask:0xf
	v_mov_b32_dpp v88, v110 row_shr:1 row_mask:0xf bank_mask:0xf
	v_mov_b32_dpp v83, v111 row_shr:2 row_mask:0xf bank_mask:0xf
	v_mov_b32_dpp v89, v111 row_shr:1 row_mask:0xf bank_mask:0xf
	v_pk_fma_f32 v[82:83], v[128:129], v[82:83], v[144:145]
	v_cvt_pk_bf16_f32 v72, v72, v73
	v_cvt_pk_bf16_f32 v73, v86, v0
	v_mov_b32_dpp v86, v84 row_ror:1 row_mask:0xf bank_mask:0xf bound_ctrl:1
	v_pk_fma_f32 v[82:83], v[136:137], v[88:89], v[82:83]
	v_mov_b32_dpp v88, v74 row_ror:1 row_mask:0xf bank_mask:0xf bound_ctrl:1
	v_pk_fma_f32 v[82:83], v[110:111], v[132:133], v[82:83]
	v_mov_b32_dpp v74, v74 row_ror:2 row_mask:0xf bank_mask:0xf bound_ctrl:1
	v_mul_f32_e32 v0, 0xbfb8aa3b, v83
	v_exp_f32_e32 v0, v0
	v_mov_b32_dpp v89, v75 row_ror:1 row_mask:0xf bank_mask:0xf bound_ctrl:1
	v_mov_b32_dpp v75, v75 row_ror:2 row_mask:0xf bank_mask:0xf bound_ctrl:1
	v_mov_b32_dpp v74, v106 row_shr:2 row_mask:0xf bank_mask:0xf
	v_add_f32_e32 v0, 1.0, v0
	v_rcp_f32_e32 v0, v0
	v_mov_b32_dpp v75, v107 row_shr:2 row_mask:0xf bank_mask:0xf
	v_mov_b32_dpp v88, v106 row_shr:1 row_mask:0xf bank_mask:0xf
	v_mov_b32_dpp v89, v107 row_shr:1 row_mask:0xf bank_mask:0xf
	v_pk_fma_f32 v[74:75], v[116:117], v[74:75], v[140:141]
	v_mul_f32_e32 v0, v83, v0
	v_pk_fma_f32 v[74:75], v[120:121], v[88:89], v[74:75]
	v_mov_b32_dpp v84, v84 row_ror:2 row_mask:0xf bank_mask:0xf bound_ctrl:1
	v_pk_fma_f32 v[74:75], v[106:107], v[124:125], v[74:75]
	v_mov_b32_dpp v85, v85 row_ror:2 row_mask:0xf bank_mask:0xf bound_ctrl:1
	v_mul_f32_e32 v0, v0, v75
	v_mul_f32_e32 v75, 0xbfb8aa3b, v82
	v_exp_f32_e32 v75, v75
	v_mov_b32_dpp v84, v108 row_shr:2 row_mask:0xf bank_mask:0xf
	v_mov_b32_dpp v85, v109 row_shr:2 row_mask:0xf bank_mask:0xf
	v_mov_b32_dpp v86, v108 row_shr:1 row_mask:0xf bank_mask:0xf
	v_add_f32_e32 v75, 1.0, v75
	v_rcp_f32_e32 v75, v75
	v_mov_b32_dpp v87, v109 row_shr:1 row_mask:0xf bank_mask:0xf
	v_pk_fma_f32 v[84:85], v[126:127], v[84:85], v[142:143]
	v_mov_b32_e32 v132, 0
	v_pk_fma_f32 v[84:85], v[134:135], v[86:87], v[84:85]
	v_mul_f32_e32 v75, v82, v75
	v_pk_fma_f32 v[84:85], v[108:109], v[130:131], v[84:85]
	v_mul_f32_e32 v74, v75, v74
	v_mul_f32_e32 v75, 0xbfb8aa3b, v85
	v_exp_f32_e32 v75, v75
	v_mov_b32_dpp v86, v76 row_ror:1 row_mask:0xf bank_mask:0xf bound_ctrl:1
	v_mov_b32_dpp v76, v76 row_ror:2 row_mask:0xf bank_mask:0xf bound_ctrl:1
	v_mov_b32_dpp v87, v77 row_ror:1 row_mask:0xf bank_mask:0xf bound_ctrl:1
	v_add_f32_e32 v75, 1.0, v75
	v_mov_b32_dpp v77, v77 row_ror:2 row_mask:0xf bank_mask:0xf bound_ctrl:1
	v_rcp_f32_e32 v75, v75
	v_mov_b32_dpp v76, v104 row_shr:2 row_mask:0xf bank_mask:0xf
	v_mov_b32_dpp v77, v105 row_shr:2 row_mask:0xf bank_mask:0xf
	v_mov_b32_dpp v86, v104 row_shr:1 row_mask:0xf bank_mask:0xf
	v_mov_b32_dpp v87, v105 row_shr:1 row_mask:0xf bank_mask:0xf
	v_pk_fma_f32 v[76:77], v[114:115], v[76:77], v[138:139]
	v_mul_f32_e32 v75, v85, v75
	v_pk_fma_f32 v[76:77], v[118:119], v[86:87], v[76:77]
	v_mov_b32_e32 v134, 0
	v_pk_fma_f32 v[76:77], v[104:105], v[122:123], v[76:77]
	v_mov_b32_e32 v135, 0
	v_mul_f32_e32 v75, v75, v77
	v_mul_f32_e32 v77, 0xbfb8aa3b, v84
	v_exp_f32_e32 v77, v77
	v_mov_b32_e32 v136, 0
	v_mov_b32_e32 v137, 0
	v_add_f32_e32 v77, 1.0, v77
	v_rcp_f32_e32 v77, v77
	s_nop 0
	v_mul_f32_e32 v77, v84, v77
	v_mul_f32_e32 v76, v77, v76
	v_cvt_pk_bf16_f32 v76, v76, v75
	v_cvt_pk_bf16_f32 v77, v74, v0
	v_add_co_u32_e32 v74, vcc, s1, v202
	global_load_dwordx4 v[92:95], v[202:203], off offset:16
	s_nop 0
	v_addc_co_u32_e32 v75, vcc, 0, v203, vcc
	global_load_dwordx4 v[116:119], v[74:75], off offset:3088
	v_add_co_u32_e32 v74, vcc, 0x15000, v202
	s_nop 1
	v_addc_co_u32_e32 v75, vcc, 0, v203, vcc
	global_load_dwordx4 v[120:123], v[74:75], off offset:2064
	global_load_dwordx4 v[128:131], v[200:201], off offset:16
	v_add_co_u32_e32 v74, vcc, 0x5000, v202
	s_nop 1
	v_addc_co_u32_e32 v75, vcc, 0, v203, vcc
	global_load_dwordx4 v[106:109], v[74:75], off offset:1552
	global_load_dwordx4 v[84:87], v[204:205], off offset:528
	v_add_co_u32_e32 v74, vcc, 0x1a000, v202
	s_nop 1
	v_addc_co_u32_e32 v75, vcc, 0, v203, vcc
	global_load_dwordx4 v[88:91], v[74:75], off offset:3600
	v_add_co_u32_e32 v74, vcc, 0x5000, v200
	s_nop 1
	v_addc_co_u32_e32 v75, vcc, 0, v201, vcc
	global_load_dwordx4 v[124:127], v[74:75], off offset:1552
	s_and_saveexec_b64 s[86:87], s[78:79]
	ds_read_b128 v[134:137], v236 offset:16
	s_or_b64 exec, exec, s[86:87]
	v_mov_b32_e32 v74, v198
	v_mov_b32_e32 v75, v198
	v_pk_mul_f32 v[62:63], v[62:63], v[74:75]
	v_pk_mul_f32 v[60:61], v[60:61], v[198:199]
	s_waitcnt lgkmcnt(0)
; #define PG8_LAS __attribute__((address_space(3)))
; __device__ __forceinline__ unsigned cvt_pk_bf16(float lo, float hi) { unsigned r; asm volatile("v_cvt_pk_bf16_f32 %0, %1, %2" : "=v"(r) : "v"(lo), "v"(hi)); return r; }
; #define PG8_ROR(src, ctrl) __builtin_bit_cast(float, __builtin_amdgcn_mov_dpp(__builtin_bit_cast(int, (float)(src)), (ctrl), 0xf, 0xf, true))
; #define PG8_DPP(old, src, ctrl) __builtin_bit_cast(float, __builtin_amdgcn_update_dpp(__builtin_bit_cast(int, (float)(old)), __builtin_bit_cast(int, (float)(src)), (ctrl), 0xf, 0xf, false))
;     __device__ __forceinline__ void operator()(f32x4 (&acc)[2][2][4][2], const Unit& u, int wr, int wc, int fr, int fq, PG8_LAS unsigned char* lds, int wid, int lane) const {
;     ...
;                     for (int bj = 0; bj < 2; ++bj) { const f32x4 cur = acc[ai][bj][m][n]; f32x4 prev;
;                         if (m > 0) prev = acc[ai][bj][m > 0 ? m - 1 : 0][n];
;                         else { prev = (f32x4){0.f, 0.f, 0.f, 0.f}; if (b > 0 && fr >= 14) prev = *(const PG8_LAS f32x4*)(X + ((b - 1) * 2 + fr - 14) * 256 + bj * HALF + wc * 32 + 8 * fq + 4 * n); }
;                         f32x4 p1, p2;
; #pragma unroll
;                         for (int j = 0; j < 4; ++j) { const float r1 = PG8_ROR(prev[j], 0x121), r2 = PG8_ROR(prev[j], 0x122);
;                             p1[j] = PG8_DPP(r1, cur[j], 0x111); p2[j] = PG8_DPP(r2, cur[j], 0x112); }
;                         c[bj] = bs[bj] + w[bj][0] * p2 + w[bj][1] * p1 + w[bj][2] * cur; }
;                     float h4[4];
; #pragma unroll
;                     for (int j = 0; j < 4; ++j) h4[j] = c[0][j] * __builtin_amdgcn_rcpf(1.0f + __expf(-c[0][j])) * c[1][j];
;                     if (n == 0) { pk0[ai][m][0] = cvt_pk_bf16(h4[0], h4[1]); pk0[ai][m][1] = cvt_pk_bf16(h4[2], h4[3]); }
;                     else { u32x4 pk; pk.x = pk0[ai][m][0]; pk.y = pk0[ai][m][1]; pk.z = cvt_pk_bf16(h4[0], h4[1]); pk.w = cvt_pk_bf16(h4[2], h4[3]);
;                         *(PG8_LAS u32x4*)(st + fr * 80 + fq * 16) = pk;
;                         const u32x4 x = *(const PG8_LAS u32x4*)(st + (lane >> 2) * 80 + (lane & 3) * 16);
;                         const int t2 = ai * HALF + wr * 64 + m * 16 + (lane >> 2), gr = grow0 + t2;
;                         if (t2 >= 2 && gr < 8192) *(u32x4*)(HM + (size_t)gr * 5504 + u.pn * 128 + wc * 32 + 8 * (lane & 3)) = x; } } }
	v_mov_b32_dpp v82, v134 row_ror:1 row_mask:0xf bank_mask:0xf bound_ctrl:1
	v_mov_b32_dpp v98, v134 row_ror:2 row_mask:0xf bank_mask:0xf bound_ctrl:1
	v_mov_b32_dpp v83, v135 row_ror:1 row_mask:0xf bank_mask:0xf bound_ctrl:1
	v_mov_b32_dpp v99, v135 row_ror:2 row_mask:0xf bank_mask:0xf bound_ctrl:1
	v_mov_b32_dpp v104, v136 row_ror:1 row_mask:0xf bank_mask:0xf bound_ctrl:1
	v_mov_b32_dpp v110, v136 row_ror:2 row_mask:0xf bank_mask:0xf bound_ctrl:1
	v_mov_b32_dpp v105, v137 row_ror:1 row_mask:0xf bank_mask:0xf bound_ctrl:1
	v_mov_b32_dpp v111, v137 row_ror:2 row_mask:0xf bank_mask:0xf bound_ctrl:1
	v_mov_b32_dpp v82, v60 row_shr:1 row_mask:0xf bank_mask:0xf
	v_mov_b32_dpp v98, v60 row_shr:2 row_mask:0xf bank_mask:0xf
	v_mov_b32_dpp v83, v61 row_shr:1 row_mask:0xf bank_mask:0xf
	v_mov_b32_dpp v99, v61 row_shr:2 row_mask:0xf bank_mask:0xf
	v_mov_b32_dpp v104, v62 row_shr:1 row_mask:0xf bank_mask:0xf
	v_mov_b32_dpp v110, v62 row_shr:2 row_mask:0xf bank_mask:0xf
	v_mov_b32_dpp v105, v63 row_shr:1 row_mask:0xf bank_mask:0xf
	v_mov_b32_dpp v111, v63 row_shr:2 row_mask:0xf bank_mask:0xf
	v_mov_b32_e32 v133, 0
	v_mov_b32_e32 v134, 0
	v_mov_b32_e32 v135, 0
	s_and_saveexec_b64 s[86:87], s[78:79]
	ds_read_b128 v[132:135], v236 offset:528
	s_or_b64 exec, exec, s[86:87]
	s_waitcnt vmcnt(4)
	v_pk_fma_f32 v[110:111], v[94:95], v[110:111], v[130:131]
	v_pk_fma_f32 v[98:99], v[92:93], v[98:99], v[128:129]
	v_pk_fma_f32 v[104:105], v[118:119], v[104:105], v[110:111]
	v_pk_fma_f32 v[82:83], v[116:117], v[82:83], v[98:99]
	v_pk_fma_f32 v[98:99], v[62:63], v[122:123], v[104:105]
	v_pk_mul_f32 v[56:57], v[56:57], v[198:199]
	v_mul_f32_e32 v0, 0xbfb8aa3b, v99
	v_exp_f32_e32 v0, v0
	s_waitcnt lgkmcnt(0)
	v_mov_b32_dpp v104, v132 row_ror:2 row_mask:0xf bank_mask:0xf bound_ctrl:1
	v_mov_b32_dpp v105, v133 row_ror:2 row_mask:0xf bank_mask:0xf bound_ctrl:1
	v_pk_mul_f32 v[58:59], v[58:59], v[74:75]
	v_mov_b32_dpp v74, v132 row_ror:1 row_mask:0xf bank_mask:0xf bound_ctrl:1
	v_mov_b32_dpp v104, v56 row_shr:2 row_mask:0xf bank_mask:0xf
	v_mov_b32_dpp v75, v133 row_ror:1 row_mask:0xf bank_mask:0xf bound_ctrl:1
	v_mov_b32_dpp v105, v57 row_shr:2 row_mask:0xf bank_mask:0xf
	v_mov_b32_dpp v114, v134 row_ror:2 row_mask:0xf bank_mask:0xf bound_ctrl:1
	v_mov_b32_dpp v115, v135 row_ror:2 row_mask:0xf bank_mask:0xf bound_ctrl:1
	v_mov_b32_dpp v74, v56 row_shr:1 row_mask:0xf bank_mask:0xf
	v_mov_b32_dpp v75, v57 row_shr:1 row_mask:0xf bank_mask:0xf
	v_mov_b32_dpp v110, v134 row_ror:1 row_mask:0xf bank_mask:0xf bound_ctrl:1
	v_mov_b32_dpp v114, v58 row_shr:2 row_mask:0xf bank_mask:0xf
	v_mov_b32_dpp v111, v135 row_ror:1 row_mask:0xf bank_mask:0xf bound_ctrl:1
	v_mov_b32_dpp v115, v59 row_shr:2 row_mask:0xf bank_mask:0xf
	s_waitcnt vmcnt(0)
	v_pk_fma_f32 v[104:105], v[106:107], v[104:105], v[124:125]
	v_add_f32_e32 v0, 1.0, v0
	v_mov_b32_dpp v110, v58 row_shr:1 row_mask:0xf bank_mask:0xf
	v_mov_b32_dpp v111, v59 row_shr:1 row_mask:0xf bank_mask:0xf
	v_pk_fma_f32 v[114:115], v[108:109], v[114:115], v[126:127]
	v_pk_fma_f32 v[74:75], v[84:85], v[74:75], v[104:105]
	v_rcp_f32_e32 v0, v0
	v_mul_f32_e32 v104, 0xbfb8aa3b, v98
	v_pk_fma_f32 v[110:111], v[86:87], v[110:111], v[114:115]
	v_exp_f32_e32 v114, v104
	v_pk_fma_f32 v[82:83], v[60:61], v[120:121], v[82:83]
	v_pk_fma_f32 v[104:105], v[58:59], v[90:91], v[110:111]
	v_mul_f32_e32 v0, v99, v0
	v_mul_f32_e32 v0, v0, v105
	v_add_f32_e32 v99, 1.0, v114
	v_mul_f32_e32 v105, 0xbfb8aa3b, v83
	v_mul_f32_e32 v110, 0xbfb8aa3b, v82
	v_rcp_f32_e32 v99, v99
	v_exp_f32_e32 v105, v105
	v_exp_f32_e32 v110, v110
	v_pk_fma_f32 v[74:75], v[56:57], v[88:89], v[74:75]
	v_mul_f32_e32 v98, v98, v99
	v_add_f32_e32 v99, 1.0, v105
	v_add_f32_e32 v105, 1.0, v110
	v_rcp_f32_e32 v105, v105
	v_rcp_f32_e32 v99, v99
	s_ashr_i32 s1, s0, 31
	v_mul_f32_e32 v98, v98, v104
	v_mul_f32_e32 v82, v82, v105
	v_mul_f32_e32 v83, v83, v99
	v_mul_f32_e32 v74, v82, v74
	v_mul_f32_e32 v75, v83, v75
	v_cvt_pk_bf16_f32 v114, v74, v75
	v_add_u32_e32 v74, s72, v235
	v_cmp_gt_i32_e32 vcc, s37, v74
	v_cvt_pk_bf16_f32 v115, v98, v0
	s_and_b64 s[88:89], s[42:43], vcc
	v_lshlrev_b32_e32 v0, 1, v182
	ds_write_b128 v240, v[112:115]
	s_and_saveexec_b64 s[86:87], s[88:89]
	s_cbranch_execz .LBB0_391
	ds_read_b128 v[110:113], v241
	v_mov_b64_e32 v[82:83], s[12:13]
	s_movk_i32 s20, 0x2b00
	v_mad_i64_i32 v[74:75], s[88:89], v74, s20, v[82:83]
	v_lshl_add_u64 v[74:75], s[0:1], 1, v[74:75]
	s_lshl_b32 s20, s97, 1
	v_lshl_add_u64 v[74:75], v[74:75], 0, s[20:21]
	v_lshl_add_u64 v[74:75], v[74:75], 0, v[0:1]
	s_waitcnt lgkmcnt(0)
	global_store_dwordx4 v[74:75], v[110:113], off
